# GU epilogue global stores marked nt (streaming act output does not displace A/B tiles in L2)
# baseline (speedup 1.0000x reference)
.Lg16_gu_k:
	s_add_i32 s8, s1, 2
	s_lshl_b32 s96, s8, 13
	s_add_i32 m0, vcc_lo, 16384
	v_lshl_add_u64 v[160:161], v[188:189], 0, s[96:97]
	global_load_lds_dwordx4 v[160:161], off
	global_load_lds_dwordx4 v[160:161], off offset:1024
	ds_read_b128 v[196:199], v246 offset:0
	ds_read_b128 v[200:203], v246 offset:1024
	ds_read_b128 v[204:207], v246 offset:2048
	ds_read_b128 v[242:245], v246 offset:3072
	s_add_i32 s8, s1, 2
	s_lshl_b32 s96, s8, 11
	v_lshl_add_u64 v[248:249], v[184:185], 0, s[96:97]
	v_lshl_add_u64 v[250:251], v[186:187], 0, s[96:97]
	s_waitcnt vmcnt(8) lgkmcnt(3)
	v_mfma_f32_16x16x32_bf16 v[112:115], v[128:131], v[196:199], v[112:115]
	v_mfma_f32_16x16x32_bf16 v[120:123], v[132:135], v[196:199], v[120:123]
	v_mfma_f32_16x16x32_bf16 v[80:83], v[136:139], v[196:199], v[80:83]
	v_mfma_f32_16x16x32_bf16 v[88:91], v[140:143], v[196:199], v[88:91]
	ds_read_b128 v[196:199], v246 offset:4096
	s_waitcnt lgkmcnt(3)
	v_mfma_f32_16x16x32_bf16 v[116:119], v[128:131], v[200:203], v[116:119]
	v_mfma_f32_16x16x32_bf16 v[124:127], v[132:135], v[200:203], v[124:127]
	v_mfma_f32_16x16x32_bf16 v[84:87], v[136:139], v[200:203], v[84:87]
	v_mfma_f32_16x16x32_bf16 v[92:95], v[140:143], v[200:203], v[92:95]
	ds_read_b128 v[200:203], v246 offset:5120
	s_waitcnt lgkmcnt(3)
	v_mfma_f32_16x16x32_bf16 v[96:99], v[128:131], v[204:207], v[96:99]
	v_mfma_f32_16x16x32_bf16 v[104:107], v[132:135], v[204:207], v[104:107]
	v_mfma_f32_16x16x32_bf16 v[64:67], v[136:139], v[204:207], v[64:67]
	v_mfma_f32_16x16x32_bf16 v[72:75], v[140:143], v[204:207], v[72:75]
	ds_read_b128 v[204:207], v246 offset:6144
	s_waitcnt lgkmcnt(3)
	v_mfma_f32_16x16x32_bf16 v[100:103], v[128:131], v[242:245], v[100:103]
	v_mfma_f32_16x16x32_bf16 v[108:111], v[132:135], v[242:245], v[108:111]
	v_mfma_f32_16x16x32_bf16 v[68:71], v[136:139], v[242:245], v[68:71]
	v_mfma_f32_16x16x32_bf16 v[76:79], v[140:143], v[242:245], v[76:79]
	ds_read_b128 v[242:245], v246 offset:7168
	s_waitcnt lgkmcnt(3)
	v_mfma_f32_16x16x32_bf16 v[48:51], v[128:131], v[196:199], v[48:51]
	v_mfma_f32_16x16x32_bf16 v[56:59], v[132:135], v[196:199], v[56:59]
	v_mfma_f32_16x16x32_bf16 v[16:19], v[136:139], v[196:199], v[16:19]
	v_mfma_f32_16x16x32_bf16 v[24:27], v[140:143], v[196:199], v[24:27]
	s_waitcnt lgkmcnt(2)
	v_mfma_f32_16x16x32_bf16 v[52:55], v[128:131], v[200:203], v[52:55]
	v_mfma_f32_16x16x32_bf16 v[60:63], v[132:135], v[200:203], v[60:63]
	v_mfma_f32_16x16x32_bf16 v[20:23], v[136:139], v[200:203], v[20:23]
	v_mfma_f32_16x16x32_bf16 v[28:31], v[140:143], v[200:203], v[28:31]
	s_waitcnt lgkmcnt(1)
	v_mfma_f32_16x16x32_bf16 v[32:35], v[128:131], v[204:207], v[32:35]
	v_mfma_f32_16x16x32_bf16 v[40:43], v[132:135], v[204:207], v[40:43]
	v_mfma_f32_16x16x32_bf16 v[0:3], v[136:139], v[204:207], v[0:3]
	v_mfma_f32_16x16x32_bf16 v[8:11], v[140:143], v[204:207], v[8:11]
	s_waitcnt lgkmcnt(0)
	v_mfma_f32_16x16x32_bf16 v[36:39], v[128:131], v[242:245], v[36:39]
	v_mfma_f32_16x16x32_bf16 v[44:47], v[132:135], v[242:245], v[44:47]
	v_mfma_f32_16x16x32_bf16 v[4:7], v[136:139], v[242:245], v[4:7]
	v_mfma_f32_16x16x32_bf16 v[12:15], v[140:143], v[242:245], v[12:15]
	global_load_dwordx4 v[128:131], v[248:249], off
	global_load_dwordx4 v[132:135], v[248:249], off offset:256
	global_load_dwordx4 v[136:139], v[250:251], off
	global_load_dwordx4 v[140:143], v[250:251], off offset:256
	s_waitcnt vmcnt(10)
	s_barrier
	s_add_i32 s8, s1, 3
	s_lshl_b32 s96, s8, 13
	s_mov_b32 m0, vcc_lo
	v_lshl_add_u64 v[160:161], v[188:189], 0, s[96:97]
	global_load_lds_dwordx4 v[160:161], off
	global_load_lds_dwordx4 v[160:161], off offset:1024
	ds_read_b128 v[196:199], v246 offset:8192
	ds_read_b128 v[200:203], v246 offset:9216
	ds_read_b128 v[204:207], v246 offset:10240
	ds_read_b128 v[242:245], v246 offset:11264
	s_add_i32 s8, s1, 3
	s_lshl_b32 s96, s8, 11
	v_lshl_add_u64 v[248:249], v[184:185], 0, s[96:97]
	v_lshl_add_u64 v[250:251], v[186:187], 0, s[96:97]
	s_waitcnt vmcnt(8) lgkmcnt(3)
	v_mfma_f32_16x16x32_bf16 v[112:115], v[144:147], v[196:199], v[112:115]
	v_mfma_f32_16x16x32_bf16 v[120:123], v[148:151], v[196:199], v[120:123]
	v_mfma_f32_16x16x32_bf16 v[80:83], v[152:155], v[196:199], v[80:83]
	v_mfma_f32_16x16x32_bf16 v[88:91], v[156:159], v[196:199], v[88:91]
	ds_read_b128 v[196:199], v246 offset:12288
	s_waitcnt lgkmcnt(3)
	v_mfma_f32_16x16x32_bf16 v[116:119], v[144:147], v[200:203], v[116:119]
	v_mfma_f32_16x16x32_bf16 v[124:127], v[148:151], v[200:203], v[124:127]
	v_mfma_f32_16x16x32_bf16 v[84:87], v[152:155], v[200:203], v[84:87]
	v_mfma_f32_16x16x32_bf16 v[92:95], v[156:159], v[200:203], v[92:95]
	ds_read_b128 v[200:203], v246 offset:13312
	s_waitcnt lgkmcnt(3)
	v_mfma_f32_16x16x32_bf16 v[96:99], v[144:147], v[204:207], v[96:99]
	v_mfma_f32_16x16x32_bf16 v[104:107], v[148:151], v[204:207], v[104:107]
	v_mfma_f32_16x16x32_bf16 v[64:67], v[152:155], v[204:207], v[64:67]
	v_mfma_f32_16x16x32_bf16 v[72:75], v[156:159], v[204:207], v[72:75]
	ds_read_b128 v[204:207], v246 offset:14336
	s_waitcnt lgkmcnt(3)
	v_mfma_f32_16x16x32_bf16 v[100:103], v[144:147], v[242:245], v[100:103]
	v_mfma_f32_16x16x32_bf16 v[108:111], v[148:151], v[242:245], v[108:111]
	v_mfma_f32_16x16x32_bf16 v[68:71], v[152:155], v[242:245], v[68:71]
	v_mfma_f32_16x16x32_bf16 v[76:79], v[156:159], v[242:245], v[76:79]
	ds_read_b128 v[242:245], v246 offset:15360
	s_waitcnt lgkmcnt(3)
	v_mfma_f32_16x16x32_bf16 v[48:51], v[144:147], v[196:199], v[48:51]
	v_mfma_f32_16x16x32_bf16 v[56:59], v[148:151], v[196:199], v[56:59]
	v_mfma_f32_16x16x32_bf16 v[16:19], v[152:155], v[196:199], v[16:19]
	v_mfma_f32_16x16x32_bf16 v[24:27], v[156:159], v[196:199], v[24:27]
	s_waitcnt lgkmcnt(2)
	v_mfma_f32_16x16x32_bf16 v[52:55], v[144:147], v[200:203], v[52:55]
	v_mfma_f32_16x16x32_bf16 v[60:63], v[148:151], v[200:203], v[60:63]
	v_mfma_f32_16x16x32_bf16 v[20:23], v[152:155], v[200:203], v[20:23]
	v_mfma_f32_16x16x32_bf16 v[28:31], v[156:159], v[200:203], v[28:31]
	s_waitcnt lgkmcnt(1)
	v_mfma_f32_16x16x32_bf16 v[32:35], v[144:147], v[204:207], v[32:35]
	v_mfma_f32_16x16x32_bf16 v[40:43], v[148:151], v[204:207], v[40:43]
	v_mfma_f32_16x16x32_bf16 v[0:3], v[152:155], v[204:207], v[0:3]
	v_mfma_f32_16x16x32_bf16 v[8:11], v[156:159], v[204:207], v[8:11]
	s_waitcnt lgkmcnt(0)
	v_mfma_f32_16x16x32_bf16 v[36:39], v[144:147], v[242:245], v[36:39]
	v_mfma_f32_16x16x32_bf16 v[44:47], v[148:151], v[242:245], v[44:47]
	v_mfma_f32_16x16x32_bf16 v[4:7], v[152:155], v[242:245], v[4:7]
	v_mfma_f32_16x16x32_bf16 v[12:15], v[156:159], v[242:245], v[12:15]
	global_load_dwordx4 v[144:147], v[248:249], off
	global_load_dwordx4 v[148:151], v[248:249], off offset:256
	global_load_dwordx4 v[152:155], v[250:251], off
	global_load_dwordx4 v[156:159], v[250:251], off offset:256
	s_waitcnt vmcnt(10)
	s_barrier
	s_add_i32 s8, s1, 4
	s_lshl_b32 s96, s8, 13
	s_add_i32 m0, vcc_lo, 8192
	v_lshl_add_u64 v[160:161], v[188:189], 0, s[96:97]
	global_load_lds_dwordx4 v[160:161], off
	global_load_lds_dwordx4 v[160:161], off offset:1024
	ds_read_b128 v[196:199], v246 offset:16384
	ds_read_b128 v[200:203], v246 offset:17408
	ds_read_b128 v[204:207], v246 offset:18432
	ds_read_b128 v[242:245], v246 offset:19456
	s_add_i32 s8, s1, 4
	s_lshl_b32 s96, s8, 11
	v_lshl_add_u64 v[248:249], v[184:185], 0, s[96:97]
	v_lshl_add_u64 v[250:251], v[186:187], 0, s[96:97]
	s_waitcnt vmcnt(8) lgkmcnt(3)
	v_mfma_f32_16x16x32_bf16 v[112:115], v[128:131], v[196:199], v[112:115]
	v_mfma_f32_16x16x32_bf16 v[120:123], v[132:135], v[196:199], v[120:123]
	v_mfma_f32_16x16x32_bf16 v[80:83], v[136:139], v[196:199], v[80:83]
	v_mfma_f32_16x16x32_bf16 v[88:91], v[140:143], v[196:199], v[88:91]
	ds_read_b128 v[196:199], v246 offset:20480
	s_waitcnt lgkmcnt(3)
	v_mfma_f32_16x16x32_bf16 v[116:119], v[128:131], v[200:203], v[116:119]
	v_mfma_f32_16x16x32_bf16 v[124:127], v[132:135], v[200:203], v[124:127]
	v_mfma_f32_16x16x32_bf16 v[84:87], v[136:139], v[200:203], v[84:87]
	v_mfma_f32_16x16x32_bf16 v[92:95], v[140:143], v[200:203], v[92:95]
	ds_read_b128 v[200:203], v246 offset:21504
	s_waitcnt lgkmcnt(3)
	v_mfma_f32_16x16x32_bf16 v[96:99], v[128:131], v[204:207], v[96:99]
	v_mfma_f32_16x16x32_bf16 v[104:107], v[132:135], v[204:207], v[104:107]
	v_mfma_f32_16x16x32_bf16 v[64:67], v[136:139], v[204:207], v[64:67]
	v_mfma_f32_16x16x32_bf16 v[72:75], v[140:143], v[204:207], v[72:75]
	ds_read_b128 v[204:207], v246 offset:22528
	s_waitcnt lgkmcnt(3)
	v_mfma_f32_16x16x32_bf16 v[100:103], v[128:131], v[242:245], v[100:103]
	v_mfma_f32_16x16x32_bf16 v[108:111], v[132:135], v[242:245], v[108:111]
	v_mfma_f32_16x16x32_bf16 v[68:71], v[136:139], v[242:245], v[68:71]
	v_mfma_f32_16x16x32_bf16 v[76:79], v[140:143], v[242:245], v[76:79]
	ds_read_b128 v[242:245], v246 offset:23552
	s_waitcnt lgkmcnt(3)
	v_mfma_f32_16x16x32_bf16 v[48:51], v[128:131], v[196:199], v[48:51]
	v_mfma_f32_16x16x32_bf16 v[56:59], v[132:135], v[196:199], v[56:59]
	v_mfma_f32_16x16x32_bf16 v[16:19], v[136:139], v[196:199], v[16:19]
	v_mfma_f32_16x16x32_bf16 v[24:27], v[140:143], v[196:199], v[24:27]
	s_waitcnt lgkmcnt(2)
	v_mfma_f32_16x16x32_bf16 v[52:55], v[128:131], v[200:203], v[52:55]
	v_mfma_f32_16x16x32_bf16 v[60:63], v[132:135], v[200:203], v[60:63]
	v_mfma_f32_16x16x32_bf16 v[20:23], v[136:139], v[200:203], v[20:23]
	v_mfma_f32_16x16x32_bf16 v[28:31], v[140:143], v[200:203], v[28:31]
	s_waitcnt lgkmcnt(1)
	v_mfma_f32_16x16x32_bf16 v[32:35], v[128:131], v[204:207], v[32:35]
	v_mfma_f32_16x16x32_bf16 v[40:43], v[132:135], v[204:207], v[40:43]
	v_mfma_f32_16x16x32_bf16 v[0:3], v[136:139], v[204:207], v[0:3]
	v_mfma_f32_16x16x32_bf16 v[8:11], v[140:143], v[204:207], v[8:11]
	s_waitcnt lgkmcnt(0)
	v_mfma_f32_16x16x32_bf16 v[36:39], v[128:131], v[242:245], v[36:39]
	v_mfma_f32_16x16x32_bf16 v[44:47], v[132:135], v[242:245], v[44:47]
	v_mfma_f32_16x16x32_bf16 v[4:7], v[136:139], v[242:245], v[4:7]
	v_mfma_f32_16x16x32_bf16 v[12:15], v[140:143], v[242:245], v[12:15]
	global_load_dwordx4 v[128:131], v[248:249], off
	global_load_dwordx4 v[132:135], v[248:249], off offset:256
	global_load_dwordx4 v[136:139], v[250:251], off
	global_load_dwordx4 v[140:143], v[250:251], off offset:256
	s_waitcnt vmcnt(10)
	s_barrier
	s_add_i32 s8, s1, 5
	s_lshl_b32 s96, s8, 13
	s_add_i32 m0, vcc_lo, 16384
	v_lshl_add_u64 v[160:161], v[188:189], 0, s[96:97]
	global_load_lds_dwordx4 v[160:161], off
	global_load_lds_dwordx4 v[160:161], off offset:1024
	ds_read_b128 v[196:199], v246 offset:0
	ds_read_b128 v[200:203], v246 offset:1024
	ds_read_b128 v[204:207], v246 offset:2048
	ds_read_b128 v[242:245], v246 offset:3072
	s_add_i32 s8, s1, 5
	s_lshl_b32 s96, s8, 11
	v_lshl_add_u64 v[248:249], v[184:185], 0, s[96:97]
	v_lshl_add_u64 v[250:251], v[186:187], 0, s[96:97]
	s_waitcnt vmcnt(8) lgkmcnt(3)
	v_mfma_f32_16x16x32_bf16 v[112:115], v[144:147], v[196:199], v[112:115]
	v_mfma_f32_16x16x32_bf16 v[120:123], v[148:151], v[196:199], v[120:123]
	v_mfma_f32_16x16x32_bf16 v[80:83], v[152:155], v[196:199], v[80:83]
	v_mfma_f32_16x16x32_bf16 v[88:91], v[156:159], v[196:199], v[88:91]
	ds_read_b128 v[196:199], v246 offset:4096
	s_waitcnt lgkmcnt(3)
	v_mfma_f32_16x16x32_bf16 v[116:119], v[144:147], v[200:203], v[116:119]
	v_mfma_f32_16x16x32_bf16 v[124:127], v[148:151], v[200:203], v[124:127]
	v_mfma_f32_16x16x32_bf16 v[84:87], v[152:155], v[200:203], v[84:87]
	v_mfma_f32_16x16x32_bf16 v[92:95], v[156:159], v[200:203], v[92:95]
	ds_read_b128 v[200:203], v246 offset:5120
	s_waitcnt lgkmcnt(3)
	v_mfma_f32_16x16x32_bf16 v[96:99], v[144:147], v[204:207], v[96:99]
	v_mfma_f32_16x16x32_bf16 v[104:107], v[148:151], v[204:207], v[104:107]
	v_mfma_f32_16x16x32_bf16 v[64:67], v[152:155], v[204:207], v[64:67]
	v_mfma_f32_16x16x32_bf16 v[72:75], v[156:159], v[204:207], v[72:75]
	ds_read_b128 v[204:207], v246 offset:6144
	s_waitcnt lgkmcnt(3)
	v_mfma_f32_16x16x32_bf16 v[100:103], v[144:147], v[242:245], v[100:103]
	v_mfma_f32_16x16x32_bf16 v[108:111], v[148:151], v[242:245], v[108:111]
	v_mfma_f32_16x16x32_bf16 v[68:71], v[152:155], v[242:245], v[68:71]
	v_mfma_f32_16x16x32_bf16 v[76:79], v[156:159], v[242:245], v[76:79]
	ds_read_b128 v[242:245], v246 offset:7168
	s_waitcnt lgkmcnt(3)
	v_mfma_f32_16x16x32_bf16 v[48:51], v[144:147], v[196:199], v[48:51]
	v_mfma_f32_16x16x32_bf16 v[56:59], v[148:151], v[196:199], v[56:59]
	v_mfma_f32_16x16x32_bf16 v[16:19], v[152:155], v[196:199], v[16:19]
	v_mfma_f32_16x16x32_bf16 v[24:27], v[156:159], v[196:199], v[24:27]
	s_waitcnt lgkmcnt(2)
	v_mfma_f32_16x16x32_bf16 v[52:55], v[144:147], v[200:203], v[52:55]
	v_mfma_f32_16x16x32_bf16 v[60:63], v[148:151], v[200:203], v[60:63]
	v_mfma_f32_16x16x32_bf16 v[20:23], v[152:155], v[200:203], v[20:23]
	v_mfma_f32_16x16x32_bf16 v[28:31], v[156:159], v[200:203], v[28:31]
	s_waitcnt lgkmcnt(1)
	v_mfma_f32_16x16x32_bf16 v[32:35], v[144:147], v[204:207], v[32:35]
	v_mfma_f32_16x16x32_bf16 v[40:43], v[148:151], v[204:207], v[40:43]
	v_mfma_f32_16x16x32_bf16 v[0:3], v[152:155], v[204:207], v[0:3]
	v_mfma_f32_16x16x32_bf16 v[8:11], v[156:159], v[204:207], v[8:11]
	s_waitcnt lgkmcnt(0)
	v_mfma_f32_16x16x32_bf16 v[36:39], v[144:147], v[242:245], v[36:39]
	v_mfma_f32_16x16x32_bf16 v[44:47], v[148:151], v[242:245], v[44:47]
	v_mfma_f32_16x16x32_bf16 v[4:7], v[152:155], v[242:245], v[4:7]
	v_mfma_f32_16x16x32_bf16 v[12:15], v[156:159], v[242:245], v[12:15]
	global_load_dwordx4 v[144:147], v[248:249], off
	global_load_dwordx4 v[148:151], v[248:249], off offset:256
	global_load_dwordx4 v[152:155], v[250:251], off
	global_load_dwordx4 v[156:159], v[250:251], off offset:256
	s_waitcnt vmcnt(10)
	s_barrier
	s_add_i32 s8, s1, 6
	s_lshl_b32 s96, s8, 13
	s_mov_b32 m0, vcc_lo
	v_lshl_add_u64 v[160:161], v[188:189], 0, s[96:97]
	global_load_lds_dwordx4 v[160:161], off
	global_load_lds_dwordx4 v[160:161], off offset:1024
	ds_read_b128 v[196:199], v246 offset:8192
	ds_read_b128 v[200:203], v246 offset:9216
	ds_read_b128 v[204:207], v246 offset:10240
	ds_read_b128 v[242:245], v246 offset:11264
	s_add_i32 s8, s1, 6
	s_lshl_b32 s96, s8, 11
	v_lshl_add_u64 v[248:249], v[184:185], 0, s[96:97]
	v_lshl_add_u64 v[250:251], v[186:187], 0, s[96:97]
	s_waitcnt vmcnt(8) lgkmcnt(3)
	v_mfma_f32_16x16x32_bf16 v[112:115], v[128:131], v[196:199], v[112:115]
	v_mfma_f32_16x16x32_bf16 v[120:123], v[132:135], v[196:199], v[120:123]
	v_mfma_f32_16x16x32_bf16 v[80:83], v[136:139], v[196:199], v[80:83]
	v_mfma_f32_16x16x32_bf16 v[88:91], v[140:143], v[196:199], v[88:91]
	ds_read_b128 v[196:199], v246 offset:12288
	s_waitcnt lgkmcnt(3)
	v_mfma_f32_16x16x32_bf16 v[116:119], v[128:131], v[200:203], v[116:119]
	v_mfma_f32_16x16x32_bf16 v[124:127], v[132:135], v[200:203], v[124:127]
	v_mfma_f32_16x16x32_bf16 v[84:87], v[136:139], v[200:203], v[84:87]
	v_mfma_f32_16x16x32_bf16 v[92:95], v[140:143], v[200:203], v[92:95]
	ds_read_b128 v[200:203], v246 offset:13312
	s_waitcnt lgkmcnt(3)
	v_mfma_f32_16x16x32_bf16 v[96:99], v[128:131], v[204:207], v[96:99]
	v_mfma_f32_16x16x32_bf16 v[104:107], v[132:135], v[204:207], v[104:107]
	v_mfma_f32_16x16x32_bf16 v[64:67], v[136:139], v[204:207], v[64:67]
	v_mfma_f32_16x16x32_bf16 v[72:75], v[140:143], v[204:207], v[72:75]
	ds_read_b128 v[204:207], v246 offset:14336
	s_waitcnt lgkmcnt(3)
	v_mfma_f32_16x16x32_bf16 v[100:103], v[128:131], v[242:245], v[100:103]
	v_mfma_f32_16x16x32_bf16 v[108:111], v[132:135], v[242:245], v[108:111]
	v_mfma_f32_16x16x32_bf16 v[68:71], v[136:139], v[242:245], v[68:71]
	v_mfma_f32_16x16x32_bf16 v[76:79], v[140:143], v[242:245], v[76:79]
	ds_read_b128 v[242:245], v246 offset:15360
	s_waitcnt lgkmcnt(3)
	v_mfma_f32_16x16x32_bf16 v[48:51], v[128:131], v[196:199], v[48:51]
	v_mfma_f32_16x16x32_bf16 v[56:59], v[132:135], v[196:199], v[56:59]
	v_mfma_f32_16x16x32_bf16 v[16:19], v[136:139], v[196:199], v[16:19]
	v_mfma_f32_16x16x32_bf16 v[24:27], v[140:143], v[196:199], v[24:27]
	s_waitcnt lgkmcnt(2)
	v_mfma_f32_16x16x32_bf16 v[52:55], v[128:131], v[200:203], v[52:55]
	v_mfma_f32_16x16x32_bf16 v[60:63], v[132:135], v[200:203], v[60:63]
	v_mfma_f32_16x16x32_bf16 v[20:23], v[136:139], v[200:203], v[20:23]
	v_mfma_f32_16x16x32_bf16 v[28:31], v[140:143], v[200:203], v[28:31]
	s_waitcnt lgkmcnt(1)
	v_mfma_f32_16x16x32_bf16 v[32:35], v[128:131], v[204:207], v[32:35]
	v_mfma_f32_16x16x32_bf16 v[40:43], v[132:135], v[204:207], v[40:43]
	v_mfma_f32_16x16x32_bf16 v[0:3], v[136:139], v[204:207], v[0:3]
	v_mfma_f32_16x16x32_bf16 v[8:11], v[140:143], v[204:207], v[8:11]
	s_waitcnt lgkmcnt(0)
	v_mfma_f32_16x16x32_bf16 v[36:39], v[128:131], v[242:245], v[36:39]
	v_mfma_f32_16x16x32_bf16 v[44:47], v[132:135], v[242:245], v[44:47]
	v_mfma_f32_16x16x32_bf16 v[4:7], v[136:139], v[242:245], v[4:7]
	v_mfma_f32_16x16x32_bf16 v[12:15], v[140:143], v[242:245], v[12:15]
	global_load_dwordx4 v[128:131], v[248:249], off
	global_load_dwordx4 v[132:135], v[248:249], off offset:256
	global_load_dwordx4 v[136:139], v[250:251], off
	global_load_dwordx4 v[140:143], v[250:251], off offset:256
	s_waitcnt vmcnt(10)
	s_barrier
	s_add_i32 s8, s1, 7
	s_lshl_b32 s96, s8, 13
	s_add_i32 m0, vcc_lo, 8192
	v_lshl_add_u64 v[160:161], v[188:189], 0, s[96:97]
	global_load_lds_dwordx4 v[160:161], off
	global_load_lds_dwordx4 v[160:161], off offset:1024
	ds_read_b128 v[196:199], v246 offset:16384
	ds_read_b128 v[200:203], v246 offset:17408
	ds_read_b128 v[204:207], v246 offset:18432
	ds_read_b128 v[242:245], v246 offset:19456
	s_add_i32 s8, s1, 7
	s_lshl_b32 s96, s8, 11
	v_lshl_add_u64 v[248:249], v[184:185], 0, s[96:97]
	v_lshl_add_u64 v[250:251], v[186:187], 0, s[96:97]
	s_waitcnt vmcnt(8) lgkmcnt(3)
	v_mfma_f32_16x16x32_bf16 v[112:115], v[144:147], v[196:199], v[112:115]
	v_mfma_f32_16x16x32_bf16 v[120:123], v[148:151], v[196:199], v[120:123]
	v_mfma_f32_16x16x32_bf16 v[80:83], v[152:155], v[196:199], v[80:83]
	v_mfma_f32_16x16x32_bf16 v[88:91], v[156:159], v[196:199], v[88:91]
	ds_read_b128 v[196:199], v246 offset:20480
	s_waitcnt lgkmcnt(3)
	v_mfma_f32_16x16x32_bf16 v[116:119], v[144:147], v[200:203], v[116:119]
	v_mfma_f32_16x16x32_bf16 v[124:127], v[148:151], v[200:203], v[124:127]
	v_mfma_f32_16x16x32_bf16 v[84:87], v[152:155], v[200:203], v[84:87]
	v_mfma_f32_16x16x32_bf16 v[92:95], v[156:159], v[200:203], v[92:95]
	ds_read_b128 v[200:203], v246 offset:21504
	s_waitcnt lgkmcnt(3)
	v_mfma_f32_16x16x32_bf16 v[96:99], v[144:147], v[204:207], v[96:99]
	v_mfma_f32_16x16x32_bf16 v[104:107], v[148:151], v[204:207], v[104:107]
	v_mfma_f32_16x16x32_bf16 v[64:67], v[152:155], v[204:207], v[64:67]
	v_mfma_f32_16x16x32_bf16 v[72:75], v[156:159], v[204:207], v[72:75]
	ds_read_b128 v[204:207], v246 offset:22528
	s_waitcnt lgkmcnt(3)
	v_mfma_f32_16x16x32_bf16 v[100:103], v[144:147], v[242:245], v[100:103]
	v_mfma_f32_16x16x32_bf16 v[108:111], v[148:151], v[242:245], v[108:111]
	v_mfma_f32_16x16x32_bf16 v[68:71], v[152:155], v[242:245], v[68:71]
	v_mfma_f32_16x16x32_bf16 v[76:79], v[156:159], v[242:245], v[76:79]
	ds_read_b128 v[242:245], v246 offset:23552
	s_waitcnt lgkmcnt(3)
	v_mfma_f32_16x16x32_bf16 v[48:51], v[144:147], v[196:199], v[48:51]
	v_mfma_f32_16x16x32_bf16 v[56:59], v[148:151], v[196:199], v[56:59]
	v_mfma_f32_16x16x32_bf16 v[16:19], v[152:155], v[196:199], v[16:19]
	v_mfma_f32_16x16x32_bf16 v[24:27], v[156:159], v[196:199], v[24:27]
	s_waitcnt lgkmcnt(2)
	v_mfma_f32_16x16x32_bf16 v[52:55], v[144:147], v[200:203], v[52:55]
	v_mfma_f32_16x16x32_bf16 v[60:63], v[148:151], v[200:203], v[60:63]
	v_mfma_f32_16x16x32_bf16 v[20:23], v[152:155], v[200:203], v[20:23]
	v_mfma_f32_16x16x32_bf16 v[28:31], v[156:159], v[200:203], v[28:31]
	s_waitcnt lgkmcnt(1)
	v_mfma_f32_16x16x32_bf16 v[32:35], v[144:147], v[204:207], v[32:35]
	v_mfma_f32_16x16x32_bf16 v[40:43], v[148:151], v[204:207], v[40:43]
	v_mfma_f32_16x16x32_bf16 v[0:3], v[152:155], v[204:207], v[0:3]
	v_mfma_f32_16x16x32_bf16 v[8:11], v[156:159], v[204:207], v[8:11]
	s_waitcnt lgkmcnt(0)
	v_mfma_f32_16x16x32_bf16 v[36:39], v[144:147], v[242:245], v[36:39]
	v_mfma_f32_16x16x32_bf16 v[44:47], v[148:151], v[242:245], v[44:47]
	v_mfma_f32_16x16x32_bf16 v[4:7], v[152:155], v[242:245], v[4:7]
	v_mfma_f32_16x16x32_bf16 v[12:15], v[156:159], v[242:245], v[12:15]
	global_load_dwordx4 v[144:147], v[248:249], off
	global_load_dwordx4 v[148:151], v[248:249], off offset:256
	global_load_dwordx4 v[152:155], v[250:251], off
	global_load_dwordx4 v[156:159], v[250:251], off offset:256
	s_waitcnt vmcnt(10)
	s_barrier
	s_add_i32 s1, s1, 6
	s_cmp_lt_u32 s1, 30
	s_cbranch_scc1 .Lg16_gu_k
	ds_read_b128 v[196:199], v246 offset:0
	ds_read_b128 v[200:203], v246 offset:1024
	ds_read_b128 v[204:207], v246 offset:2048
	ds_read_b128 v[242:245], v246 offset:3072
	s_waitcnt vmcnt(6) lgkmcnt(3)
	v_mfma_f32_16x16x32_bf16 v[112:115], v[128:131], v[196:199], v[112:115]
	v_mfma_f32_16x16x32_bf16 v[120:123], v[132:135], v[196:199], v[120:123]
	v_mfma_f32_16x16x32_bf16 v[80:83], v[136:139], v[196:199], v[80:83]
	v_mfma_f32_16x16x32_bf16 v[88:91], v[140:143], v[196:199], v[88:91]
	ds_read_b128 v[196:199], v246 offset:4096
	s_waitcnt lgkmcnt(3)
	v_mfma_f32_16x16x32_bf16 v[116:119], v[128:131], v[200:203], v[116:119]
	v_mfma_f32_16x16x32_bf16 v[124:127], v[132:135], v[200:203], v[124:127]
	v_mfma_f32_16x16x32_bf16 v[84:87], v[136:139], v[200:203], v[84:87]
	v_mfma_f32_16x16x32_bf16 v[92:95], v[140:143], v[200:203], v[92:95]
	ds_read_b128 v[200:203], v246 offset:5120
	s_waitcnt lgkmcnt(3)
	v_mfma_f32_16x16x32_bf16 v[96:99], v[128:131], v[204:207], v[96:99]
	v_mfma_f32_16x16x32_bf16 v[104:107], v[132:135], v[204:207], v[104:107]
	v_mfma_f32_16x16x32_bf16 v[64:67], v[136:139], v[204:207], v[64:67]
	v_mfma_f32_16x16x32_bf16 v[72:75], v[140:143], v[204:207], v[72:75]
	ds_read_b128 v[204:207], v246 offset:6144
	s_waitcnt lgkmcnt(3)
	v_mfma_f32_16x16x32_bf16 v[100:103], v[128:131], v[242:245], v[100:103]
	v_mfma_f32_16x16x32_bf16 v[108:111], v[132:135], v[242:245], v[108:111]
	v_mfma_f32_16x16x32_bf16 v[68:71], v[136:139], v[242:245], v[68:71]
	v_mfma_f32_16x16x32_bf16 v[76:79], v[140:143], v[242:245], v[76:79]
	ds_read_b128 v[242:245], v246 offset:7168
	s_waitcnt lgkmcnt(3)
	v_mfma_f32_16x16x32_bf16 v[48:51], v[128:131], v[196:199], v[48:51]
	v_mfma_f32_16x16x32_bf16 v[56:59], v[132:135], v[196:199], v[56:59]
	v_mfma_f32_16x16x32_bf16 v[16:19], v[136:139], v[196:199], v[16:19]
	v_mfma_f32_16x16x32_bf16 v[24:27], v[140:143], v[196:199], v[24:27]
	s_waitcnt lgkmcnt(2)
	v_mfma_f32_16x16x32_bf16 v[52:55], v[128:131], v[200:203], v[52:55]
	v_mfma_f32_16x16x32_bf16 v[60:63], v[132:135], v[200:203], v[60:63]
	v_mfma_f32_16x16x32_bf16 v[20:23], v[136:139], v[200:203], v[20:23]
	v_mfma_f32_16x16x32_bf16 v[28:31], v[140:143], v[200:203], v[28:31]
	s_waitcnt lgkmcnt(1)
	v_mfma_f32_16x16x32_bf16 v[32:35], v[128:131], v[204:207], v[32:35]
	v_mfma_f32_16x16x32_bf16 v[40:43], v[132:135], v[204:207], v[40:43]
	v_mfma_f32_16x16x32_bf16 v[0:3], v[136:139], v[204:207], v[0:3]
	v_mfma_f32_16x16x32_bf16 v[8:11], v[140:143], v[204:207], v[8:11]
	s_waitcnt lgkmcnt(0)
	v_mfma_f32_16x16x32_bf16 v[36:39], v[128:131], v[242:245], v[36:39]
	v_mfma_f32_16x16x32_bf16 v[44:47], v[132:135], v[242:245], v[44:47]
	v_mfma_f32_16x16x32_bf16 v[4:7], v[136:139], v[242:245], v[4:7]
	v_mfma_f32_16x16x32_bf16 v[12:15], v[140:143], v[242:245], v[12:15]
	s_waitcnt vmcnt(4)
	s_barrier
	ds_read_b128 v[196:199], v246 offset:8192
	ds_read_b128 v[200:203], v246 offset:9216
	ds_read_b128 v[204:207], v246 offset:10240
	ds_read_b128 v[242:245], v246 offset:11264
	s_waitcnt vmcnt(0) lgkmcnt(3)
	v_mfma_f32_16x16x32_bf16 v[112:115], v[144:147], v[196:199], v[112:115]
	v_mfma_f32_16x16x32_bf16 v[120:123], v[148:151], v[196:199], v[120:123]
	v_mfma_f32_16x16x32_bf16 v[80:83], v[152:155], v[196:199], v[80:83]
	v_mfma_f32_16x16x32_bf16 v[88:91], v[156:159], v[196:199], v[88:91]
	ds_read_b128 v[196:199], v246 offset:12288
	s_waitcnt lgkmcnt(3)
	v_mfma_f32_16x16x32_bf16 v[116:119], v[144:147], v[200:203], v[116:119]
	v_mfma_f32_16x16x32_bf16 v[124:127], v[148:151], v[200:203], v[124:127]
	v_mfma_f32_16x16x32_bf16 v[84:87], v[152:155], v[200:203], v[84:87]
	v_mfma_f32_16x16x32_bf16 v[92:95], v[156:159], v[200:203], v[92:95]
	ds_read_b128 v[200:203], v246 offset:13312
	s_waitcnt lgkmcnt(3)
	v_mfma_f32_16x16x32_bf16 v[96:99], v[144:147], v[204:207], v[96:99]
	v_mfma_f32_16x16x32_bf16 v[104:107], v[148:151], v[204:207], v[104:107]
	v_mfma_f32_16x16x32_bf16 v[64:67], v[152:155], v[204:207], v[64:67]
	v_mfma_f32_16x16x32_bf16 v[72:75], v[156:159], v[204:207], v[72:75]
	ds_read_b128 v[204:207], v246 offset:14336
	s_waitcnt lgkmcnt(3)
	v_mfma_f32_16x16x32_bf16 v[100:103], v[144:147], v[242:245], v[100:103]
	v_mfma_f32_16x16x32_bf16 v[108:111], v[148:151], v[242:245], v[108:111]
	v_mfma_f32_16x16x32_bf16 v[68:71], v[152:155], v[242:245], v[68:71]
	v_mfma_f32_16x16x32_bf16 v[76:79], v[156:159], v[242:245], v[76:79]
	ds_read_b128 v[242:245], v246 offset:15360
	v_permlane16_swap_b32_e32 v112, v116
	v_permlane16_swap_b32_e32 v113, v117
	v_permlane16_swap_b32_e32 v114, v118
	v_permlane16_swap_b32_e32 v115, v119
	v_permlane16_swap_b32_e32 v120, v124
	v_permlane16_swap_b32_e32 v121, v125
	v_permlane16_swap_b32_e32 v122, v126
	v_permlane16_swap_b32_e32 v123, v127
	v_permlane16_swap_b32_e32 v80, v84
	v_permlane16_swap_b32_e32 v81, v85
	v_permlane16_swap_b32_e32 v82, v86
	v_permlane16_swap_b32_e32 v83, v87
	v_permlane16_swap_b32_e32 v88, v92
	v_permlane16_swap_b32_e32 v89, v93
	v_permlane16_swap_b32_e32 v90, v94
	v_permlane16_swap_b32_e32 v91, v95
	v_permlane32_swap_b32_e32 v112, v116
	v_permlane32_swap_b32_e32 v113, v117
	v_permlane32_swap_b32_e32 v114, v118
	v_permlane32_swap_b32_e32 v115, v119
	v_permlane32_swap_b32_e32 v120, v124
	v_permlane32_swap_b32_e32 v121, v125
	v_permlane32_swap_b32_e32 v122, v126
	v_permlane32_swap_b32_e32 v123, v127
	v_permlane32_swap_b32_e32 v80, v84
	v_permlane32_swap_b32_e32 v81, v85
	v_permlane32_swap_b32_e32 v82, v86
	v_permlane32_swap_b32_e32 v83, v87
	v_permlane32_swap_b32_e32 v88, v92
	v_permlane32_swap_b32_e32 v89, v93
	v_permlane32_swap_b32_e32 v90, v94
	v_permlane32_swap_b32_e32 v91, v95
	s_waitcnt lgkmcnt(3)
	v_mfma_f32_16x16x32_bf16 v[48:51], v[144:147], v[196:199], v[48:51]
	v_mfma_f32_16x16x32_bf16 v[56:59], v[148:151], v[196:199], v[56:59]
	v_mfma_f32_16x16x32_bf16 v[16:19], v[152:155], v[196:199], v[16:19]
	v_mfma_f32_16x16x32_bf16 v[24:27], v[156:159], v[196:199], v[24:27]
	s_waitcnt lgkmcnt(2)
	v_mfma_f32_16x16x32_bf16 v[52:55], v[144:147], v[200:203], v[52:55]
	v_mfma_f32_16x16x32_bf16 v[60:63], v[148:151], v[200:203], v[60:63]
	v_mfma_f32_16x16x32_bf16 v[20:23], v[152:155], v[200:203], v[20:23]
	v_mfma_f32_16x16x32_bf16 v[28:31], v[156:159], v[200:203], v[28:31]
	v_permlane16_swap_b32_e32 v96, v100
	v_permlane16_swap_b32_e32 v97, v101
	v_permlane16_swap_b32_e32 v98, v102
	v_permlane16_swap_b32_e32 v99, v103
	v_permlane16_swap_b32_e32 v104, v108
	v_permlane16_swap_b32_e32 v105, v109
	v_permlane16_swap_b32_e32 v106, v110
	v_permlane16_swap_b32_e32 v107, v111
	v_permlane16_swap_b32_e32 v64, v68
	v_permlane16_swap_b32_e32 v65, v69
	v_permlane16_swap_b32_e32 v66, v70
	v_permlane16_swap_b32_e32 v67, v71
	v_permlane16_swap_b32_e32 v72, v76
	v_permlane16_swap_b32_e32 v73, v77
	v_permlane16_swap_b32_e32 v74, v78
	v_permlane16_swap_b32_e32 v75, v79
	v_permlane32_swap_b32_e32 v96, v100
	v_permlane32_swap_b32_e32 v97, v101
	v_permlane32_swap_b32_e32 v98, v102
	v_permlane32_swap_b32_e32 v99, v103
	v_permlane32_swap_b32_e32 v104, v108
	v_permlane32_swap_b32_e32 v105, v109
	v_permlane32_swap_b32_e32 v106, v110
	v_permlane32_swap_b32_e32 v107, v111
	v_permlane32_swap_b32_e32 v64, v68
	v_permlane32_swap_b32_e32 v65, v69
	v_permlane32_swap_b32_e32 v66, v70
	v_permlane32_swap_b32_e32 v67, v71
	v_permlane32_swap_b32_e32 v72, v76
	v_permlane32_swap_b32_e32 v73, v77
	v_permlane32_swap_b32_e32 v74, v78
	v_permlane32_swap_b32_e32 v75, v79
	s_waitcnt lgkmcnt(1)
	v_mfma_f32_16x16x32_bf16 v[32:35], v[144:147], v[204:207], v[32:35]
	v_mfma_f32_16x16x32_bf16 v[40:43], v[148:151], v[204:207], v[40:43]
	v_mfma_f32_16x16x32_bf16 v[0:3], v[152:155], v[204:207], v[0:3]
	v_mfma_f32_16x16x32_bf16 v[8:11], v[156:159], v[204:207], v[8:11]
	s_waitcnt lgkmcnt(0)
	v_mfma_f32_16x16x32_bf16 v[36:39], v[144:147], v[242:245], v[36:39]
	v_mfma_f32_16x16x32_bf16 v[44:47], v[148:151], v[242:245], v[44:47]
	v_mfma_f32_16x16x32_bf16 v[4:7], v[152:155], v[242:245], v[4:7]
	v_mfma_f32_16x16x32_bf16 v[12:15], v[156:159], v[242:245], v[12:15]
	v_permlane16_swap_b32_e32 v48, v52
	v_permlane16_swap_b32_e32 v49, v53
	v_permlane16_swap_b32_e32 v50, v54
	v_permlane16_swap_b32_e32 v51, v55
	v_permlane16_swap_b32_e32 v56, v60
	v_permlane16_swap_b32_e32 v57, v61
	v_permlane16_swap_b32_e32 v58, v62
	v_permlane16_swap_b32_e32 v59, v63
	v_permlane16_swap_b32_e32 v16, v20
	v_permlane16_swap_b32_e32 v17, v21
	v_permlane16_swap_b32_e32 v18, v22
	v_permlane16_swap_b32_e32 v19, v23
	v_permlane16_swap_b32_e32 v24, v28
	v_permlane16_swap_b32_e32 v25, v29
	v_permlane16_swap_b32_e32 v26, v30
	v_permlane16_swap_b32_e32 v27, v31
	v_permlane32_swap_b32_e32 v48, v52
	v_permlane32_swap_b32_e32 v49, v53
	v_permlane32_swap_b32_e32 v50, v54
	v_permlane32_swap_b32_e32 v51, v55
	v_permlane32_swap_b32_e32 v56, v60
	v_permlane32_swap_b32_e32 v57, v61
	v_permlane32_swap_b32_e32 v58, v62
	v_permlane32_swap_b32_e32 v59, v63
	v_permlane32_swap_b32_e32 v16, v20
	v_permlane32_swap_b32_e32 v17, v21
	v_permlane32_swap_b32_e32 v18, v22
	v_permlane32_swap_b32_e32 v19, v23
	v_permlane32_swap_b32_e32 v24, v28
	v_permlane32_swap_b32_e32 v25, v29
	v_permlane32_swap_b32_e32 v26, v30
	v_permlane32_swap_b32_e32 v27, v31
	s_barrier
	s_nop 7
	v_permlane16_swap_b32_e32 v32, v36
	v_permlane16_swap_b32_e32 v33, v37
	v_permlane16_swap_b32_e32 v34, v38
	v_permlane16_swap_b32_e32 v35, v39
	v_permlane16_swap_b32_e32 v40, v44
	v_permlane16_swap_b32_e32 v41, v45
	v_permlane16_swap_b32_e32 v42, v46
	v_permlane16_swap_b32_e32 v43, v47
	v_permlane16_swap_b32_e32 v0, v4
	v_permlane16_swap_b32_e32 v1, v5
	v_permlane16_swap_b32_e32 v2, v6
	v_permlane16_swap_b32_e32 v3, v7
	v_permlane16_swap_b32_e32 v8, v12
	v_permlane16_swap_b32_e32 v9, v13
	v_permlane16_swap_b32_e32 v10, v14
	v_permlane16_swap_b32_e32 v11, v15
	v_permlane32_swap_b32_e32 v32, v36
	v_permlane32_swap_b32_e32 v33, v37
	v_permlane32_swap_b32_e32 v34, v38
	v_permlane32_swap_b32_e32 v35, v39
	v_permlane32_swap_b32_e32 v40, v44
	v_permlane32_swap_b32_e32 v41, v45
	v_permlane32_swap_b32_e32 v42, v46
	v_permlane32_swap_b32_e32 v43, v47
	v_permlane32_swap_b32_e32 v0, v4
	v_permlane32_swap_b32_e32 v1, v5
	v_permlane32_swap_b32_e32 v2, v6
	v_permlane32_swap_b32_e32 v3, v7
	v_permlane32_swap_b32_e32 v8, v12
	v_permlane32_swap_b32_e32 v9, v13
	v_permlane32_swap_b32_e32 v10, v14
	v_permlane32_swap_b32_e32 v11, v15
	s_waitcnt vmcnt(0)
	s_waitcnt vmcnt(0)
	v_mul_f32_e32 v133, 0xbfb8aa3b, v112
	v_exp_f32_e32 v133, v133
	s_movk_i32 s1, 0x2400
	v_mul_lo_u32 v128, v238, s1
	v_lshl_or_b32 v131, s0, 6, v181
	v_add_f32_e32 v133, 1.0, v133
	v_lshl_or_b32 v132, v239, 1, v128
	v_and_b32_e32 v129, 0xffffffc0, v237
	v_lshl_or_b32 v128, v181, 1, v128
	v_rcp_f32_e32 v135, v133
	s_nop 0
	v_mul_f32_e32 v112, v112, v135
	v_mul_f32_e32 v96, v96, v112
	v_cvt_pk_bf16_f32 v112, v96, s0
	s_movk_i32 s0, 0x240
	v_mad_u32_u24 v96, v183, s0, v132
	ds_write_b16 v96, v112
	v_mul_f32_e32 v112, 0xbfb8aa3b, v113
	v_exp_f32_e32 v112, v112
	v_lshl_add_u32 v130, s7, 8, v129
	v_lshrrev_b32_e32 v129, 2, v240
	v_mad_u32_u24 v128, v129, s42, v128
	v_add_f32_e32 v112, 1.0, v112
	v_rcp_f32_e32 v133, v112
	s_nop 0
	v_mul_f32_e32 v112, v113, v133
	v_mul_f32_e32 v97, v97, v112
	v_cvt_pk_bf16_f32 v97, v97, s0
	ds_write_b16 v96, v97 offset:144
	v_mul_f32_e32 v97, 0xbfb8aa3b, v114
	v_exp_f32_e32 v97, v97
	s_nop 0
	v_add_f32_e32 v97, 1.0, v97
	v_rcp_f32_e32 v113, v97
	s_nop 0
	v_mul_f32_e32 v97, v114, v113
	v_mul_f32_e32 v97, v98, v97
	v_cvt_pk_bf16_f32 v97, v97, s0
	ds_write_b16 v96, v97 offset:288
	v_mul_f32_e32 v97, 0xbfb8aa3b, v115
	v_exp_f32_e32 v97, v97
	s_nop 0
	v_add_f32_e32 v97, 1.0, v97
	v_rcp_f32_e32 v112, v97
	s_nop 0
	v_mul_f32_e32 v97, v115, v112
	v_mul_f32_e32 v97, v99, v97
	v_cvt_pk_bf16_f32 v97, v97, s0
	ds_write_b16 v96, v97 offset:432
	v_mul_f32_e32 v97, 0xbfb8aa3b, v116
	v_exp_f32_e32 v97, v97
	s_nop 0
	v_add_f32_e32 v97, 1.0, v97
	v_rcp_f32_e32 v99, v97
	s_nop 0
	v_mul_f32_e32 v97, v116, v99
	v_mul_f32_e32 v97, v100, v97
	v_cvt_pk_bf16_f32 v97, v97, s0
	ds_write_b16 v96, v97 offset:1152
	v_mul_f32_e32 v97, 0xbfb8aa3b, v117
	v_exp_f32_e32 v97, v97
	s_nop 0
	v_add_f32_e32 v97, 1.0, v97
	v_rcp_f32_e32 v99, v97
	s_nop 0
	v_mul_f32_e32 v97, v117, v99
	v_mul_f32_e32 v97, v101, v97
	v_cvt_pk_bf16_f32 v97, v97, s0
	ds_write_b16 v96, v97 offset:1296
	v_mul_f32_e32 v97, 0xbfb8aa3b, v118
	v_exp_f32_e32 v97, v97
	s_nop 0
	v_add_f32_e32 v97, 1.0, v97
	v_rcp_f32_e32 v99, v97
	s_nop 0
	v_mul_f32_e32 v97, v118, v99
	v_mul_f32_e32 v97, v102, v97
	v_cvt_pk_bf16_f32 v97, v97, s0
	ds_write_b16 v96, v97 offset:1440
	v_mul_f32_e32 v97, 0xbfb8aa3b, v119
	v_exp_f32_e32 v97, v97
	s_nop 0
	v_add_f32_e32 v97, 1.0, v97
	v_rcp_f32_e32 v99, v97
	s_nop 0
	v_mul_f32_e32 v97, v119, v99
	v_mul_f32_e32 v97, v103, v97
	v_cvt_pk_bf16_f32 v97, v97, s0
	ds_write_b16 v96, v97 offset:1584
	v_mul_f32_e32 v97, 0xbfb8aa3b, v120
	v_exp_f32_e32 v97, v97
	s_nop 0
	v_add_f32_e32 v97, 1.0, v97
	v_rcp_f32_e32 v99, v97
	s_nop 0
	v_mul_f32_e32 v97, v120, v99
	v_mul_f32_e32 v97, v104, v97
	v_cvt_pk_bf16_f32 v97, v97, s0
	ds_write_b16 v96, v97 offset:2304
	v_mul_f32_e32 v97, 0xbfb8aa3b, v121
	v_exp_f32_e32 v97, v97
	s_nop 0
	v_add_f32_e32 v97, 1.0, v97
	v_rcp_f32_e32 v99, v97
	s_nop 0
	v_mul_f32_e32 v97, v121, v99
	v_mul_f32_e32 v97, v105, v97
	v_cvt_pk_bf16_f32 v97, v97, s0
	ds_write_b16 v96, v97 offset:2448
	v_mul_f32_e32 v97, 0xbfb8aa3b, v122
	v_exp_f32_e32 v97, v97
	s_nop 0
	v_add_f32_e32 v97, 1.0, v97
	v_rcp_f32_e32 v99, v97
	s_nop 0
	v_mul_f32_e32 v97, v122, v99
	v_mul_f32_e32 v97, v106, v97
	v_cvt_pk_bf16_f32 v97, v97, s0
	ds_write_b16 v96, v97 offset:2592
	v_mul_f32_e32 v97, 0xbfb8aa3b, v123
	v_exp_f32_e32 v97, v97
	s_nop 0
	v_add_f32_e32 v97, 1.0, v97
	v_rcp_f32_e32 v99, v97
	s_nop 0
	v_mul_f32_e32 v97, v123, v99
	v_mul_f32_e32 v97, v107, v97
	v_cvt_pk_bf16_f32 v97, v97, s0
	ds_write_b16 v96, v97 offset:2736
	v_mul_f32_e32 v97, 0xbfb8aa3b, v124
	v_exp_f32_e32 v97, v97
	s_nop 0
	v_add_f32_e32 v97, 1.0, v97
	v_rcp_f32_e32 v99, v97
	s_nop 0
	v_mul_f32_e32 v97, v124, v99
	v_mul_f32_e32 v97, v108, v97
	v_cvt_pk_bf16_f32 v97, v97, s0
	ds_write_b16 v96, v97 offset:3456
	v_mul_f32_e32 v97, 0xbfb8aa3b, v125
	v_exp_f32_e32 v97, v97
	s_nop 0
	v_add_f32_e32 v97, 1.0, v97
	v_rcp_f32_e32 v99, v97
	s_nop 0
	v_mul_f32_e32 v97, v125, v99
	v_mul_f32_e32 v97, v109, v97
	v_cvt_pk_bf16_f32 v97, v97, s0
	ds_write_b16 v96, v97 offset:3600
	v_mul_f32_e32 v97, 0xbfb8aa3b, v126
	v_exp_f32_e32 v97, v97
	s_nop 0
	v_add_f32_e32 v97, 1.0, v97
	v_rcp_f32_e32 v99, v97
	s_nop 0
	v_mul_f32_e32 v97, v126, v99
	v_mul_f32_e32 v97, v110, v97
	v_cvt_pk_bf16_f32 v97, v97, s0
	ds_write_b16 v96, v97 offset:3744
	v_mul_f32_e32 v97, 0xbfb8aa3b, v127
	v_exp_f32_e32 v97, v97
	s_nop 0
	v_add_f32_e32 v97, 1.0, v97
	v_rcp_f32_e32 v99, v97
	s_nop 0
	v_mul_f32_e32 v97, v127, v99
	v_mul_f32_e32 v97, v111, v97
	v_cvt_pk_bf16_f32 v97, v97, s0
	ds_write_b16 v96, v97 offset:3888
	v_mul_f32_e32 v97, 0xbfb8aa3b, v80
	v_exp_f32_e32 v97, v97
	s_nop 0
	v_add_f32_e32 v97, 1.0, v97
	v_rcp_f32_e32 v99, v97
	s_nop 0
	v_mul_f32_e32 v80, v80, v99
	v_mul_f32_e32 v64, v64, v80
	v_cvt_pk_bf16_f32 v64, v64, s0
	ds_write_b16 v96, v64 offset:4608
	v_mul_f32_e32 v64, 0xbfb8aa3b, v81
	v_exp_f32_e32 v64, v64
	s_nop 0
	v_add_f32_e32 v64, 1.0, v64
	v_rcp_f32_e32 v97, v64
	s_nop 0
	v_mul_f32_e32 v64, v81, v97
	v_mul_f32_e32 v64, v65, v64
	v_cvt_pk_bf16_f32 v64, v64, s0
	ds_write_b16 v96, v64 offset:4752
	v_mul_f32_e32 v64, 0xbfb8aa3b, v82
	v_exp_f32_e32 v64, v64
	s_nop 0
	v_add_f32_e32 v64, 1.0, v64
	v_rcp_f32_e32 v80, v64
	s_nop 0
	v_mul_f32_e32 v64, v82, v80
	v_mul_f32_e32 v64, v66, v64
	v_cvt_pk_bf16_f32 v64, v64, s0
	ds_write_b16 v96, v64 offset:4896
	v_mul_f32_e32 v64, 0xbfb8aa3b, v83
	v_exp_f32_e32 v64, v64
	s_nop 0
	v_add_f32_e32 v64, 1.0, v64
	v_rcp_f32_e32 v66, v64
	s_nop 0
	v_mul_f32_e32 v64, v83, v66
	v_mul_f32_e32 v64, v67, v64
	v_cvt_pk_bf16_f32 v64, v64, s0
	ds_write_b16 v96, v64 offset:5040
	v_mul_f32_e32 v64, 0xbfb8aa3b, v84
	v_exp_f32_e32 v64, v64
	s_nop 0
	v_add_f32_e32 v64, 1.0, v64
	v_rcp_f32_e32 v66, v64
	s_nop 0
	v_mul_f32_e32 v64, v84, v66
	v_mul_f32_e32 v64, v68, v64
	v_cvt_pk_bf16_f32 v64, v64, s0
	ds_write_b16 v96, v64 offset:5760
	v_mul_f32_e32 v64, 0xbfb8aa3b, v85
	v_exp_f32_e32 v64, v64
	s_nop 0
	v_add_f32_e32 v64, 1.0, v64
	v_rcp_f32_e32 v66, v64
	s_nop 0
	v_mul_f32_e32 v64, v85, v66
	v_mul_f32_e32 v64, v69, v64
	v_cvt_pk_bf16_f32 v64, v64, s0
	ds_write_b16 v96, v64 offset:5904
	v_mul_f32_e32 v64, 0xbfb8aa3b, v86
	v_exp_f32_e32 v64, v64
	s_nop 0
	v_add_f32_e32 v64, 1.0, v64
	v_rcp_f32_e32 v66, v64
	s_nop 0
	v_mul_f32_e32 v64, v86, v66
	v_mul_f32_e32 v64, v70, v64
	v_cvt_pk_bf16_f32 v64, v64, s0
	ds_write_b16 v96, v64 offset:6048
	v_mul_f32_e32 v64, 0xbfb8aa3b, v87
	v_exp_f32_e32 v64, v64
	s_nop 0
	v_add_f32_e32 v64, 1.0, v64
	v_rcp_f32_e32 v66, v64
	s_nop 0
	v_mul_f32_e32 v64, v87, v66
	v_mul_f32_e32 v64, v71, v64
	v_cvt_pk_bf16_f32 v64, v64, s0
	ds_write_b16 v96, v64 offset:6192
	v_mul_f32_e32 v64, 0xbfb8aa3b, v88
	v_exp_f32_e32 v64, v64
	v_ashrrev_i32_e32 v71, 5, v130
	v_or_b32_e32 v70, 1, v71
	v_add_f32_e32 v64, 1.0, v64
	v_rcp_f32_e32 v66, v64
	s_nop 0
	v_mul_f32_e32 v64, v88, v66
	v_mul_f32_e32 v64, v72, v64
	v_cvt_pk_bf16_f32 v64, v64, s0
	ds_write_b16 v96, v64 offset:6912
	v_mul_f32_e32 v64, 0xbfb8aa3b, v89
	v_exp_f32_e32 v64, v64
	s_nop 0
	v_add_f32_e32 v64, 1.0, v64
	v_rcp_f32_e32 v66, v64
	s_nop 0
	v_mul_f32_e32 v64, v89, v66
	v_mul_f32_e32 v64, v73, v64
	v_cvt_pk_bf16_f32 v64, v64, s0
	ds_write_b16 v96, v64 offset:7056
	v_mul_f32_e32 v64, 0xbfb8aa3b, v90
	v_exp_f32_e32 v64, v64
	s_nop 0
	v_add_f32_e32 v64, 1.0, v64
	v_rcp_f32_e32 v66, v64
	s_nop 0
	v_mul_f32_e32 v64, v90, v66
	v_mul_f32_e32 v64, v74, v64
	v_cvt_pk_bf16_f32 v64, v64, s0
	ds_write_b16 v96, v64 offset:7200
	v_mul_f32_e32 v64, 0xbfb8aa3b, v91
	v_exp_f32_e32 v64, v64
	s_nop 0
	v_add_f32_e32 v64, 1.0, v64
	v_rcp_f32_e32 v66, v64
	s_nop 0
	v_mul_f32_e32 v64, v91, v66
	v_mul_f32_e32 v64, v75, v64
	v_cvt_pk_bf16_f32 v64, v64, s0
	ds_write_b16 v96, v64 offset:7344
	v_mul_f32_e32 v64, 0xbfb8aa3b, v92
	v_exp_f32_e32 v64, v64
	s_nop 0
	v_add_f32_e32 v64, 1.0, v64
	v_rcp_f32_e32 v66, v64
	s_nop 0
	v_mul_f32_e32 v64, v92, v66
	v_mul_f32_e32 v64, v76, v64
	v_cvt_pk_bf16_f32 v64, v64, s0
	ds_write_b16 v96, v64 offset:8064
	v_mul_f32_e32 v64, 0xbfb8aa3b, v93
	v_exp_f32_e32 v64, v64
	s_nop 0
	v_add_f32_e32 v64, 1.0, v64
	v_rcp_f32_e32 v66, v64
	s_nop 0
	v_mul_f32_e32 v64, v93, v66
	v_mul_f32_e32 v64, v77, v64
	v_cvt_pk_bf16_f32 v64, v64, s0
	ds_write_b16 v96, v64 offset:8208
	v_mul_f32_e32 v64, 0xbfb8aa3b, v94
	v_exp_f32_e32 v64, v64
	s_nop 0
	v_add_f32_e32 v64, 1.0, v64
	v_rcp_f32_e32 v66, v64
	s_nop 0
	v_mul_f32_e32 v64, v94, v66
	v_mul_f32_e32 v64, v78, v64
	v_cvt_pk_bf16_f32 v64, v64, s0
	ds_write_b16 v96, v64 offset:8352
	v_mul_f32_e32 v64, 0xbfb8aa3b, v95
	v_exp_f32_e32 v64, v64
	s_nop 0
	v_add_f32_e32 v64, 1.0, v64
	v_rcp_f32_e32 v66, v64
	s_nop 0
	v_mul_f32_e32 v64, v95, v66
	v_mul_f32_e32 v64, v79, v64
	v_cvt_pk_bf16_f32 v64, v64, s0
	ds_write_b16 v96, v64 offset:8496
	v_ashrrev_i32_e32 v68, 4, v131
	s_waitcnt lgkmcnt(0)
	v_ashrrev_i32_e32 v69, 31, v68
	ds_read_b128 v[72:75], v128
	v_mad_i64_i32 v[64:65], s[0:1], v71, s23, v[68:69]
	v_lshlrev_b64 v[64:65], 10, v[64:65]
	v_lshlrev_b32_e32 v66, 6, v181
	v_lshl_add_u64 v[64:65], s[66:67], 0, v[64:65]
	v_and_b32_e32 v176, 0x200, v66
	v_lshl_add_u64 v[76:77], v[64:65], 0, v[176:177]
	v_lshlrev_b32_e32 v66, 4, v129
	v_mov_b32_e32 v67, v177
	v_lshl_add_u64 v[64:65], v[76:77], 0, v[66:67]
	s_waitcnt lgkmcnt(0)
	global_store_dwordx4 v[64:65], v[72:75], off nt
	ds_read_b128 v[72:75], v128 offset:2304
	v_or_b32_e32 v64, 0x100, v66
	v_mov_b32_e32 v65, v177
	v_lshl_add_u64 v[76:77], v[76:77], 0, v[64:65]
	s_waitcnt lgkmcnt(0)
	global_store_dwordx4 v[76:77], v[72:75], off nt
	ds_read_b128 v[72:75], v128 offset:4608
	v_mad_i64_i32 v[76:77], s[0:1], v70, s23, v[68:69]
	v_lshlrev_b64 v[76:77], 10, v[76:77]
	v_lshl_add_u64 v[76:77], s[66:67], 0, v[76:77]
	v_lshl_add_u64 v[76:77], v[76:77], 0, v[176:177]
	v_lshl_add_u64 v[78:79], v[76:77], 0, v[66:67]
	v_mul_f32_e32 v69, 0xbfb8aa3b, v48
	s_waitcnt lgkmcnt(0)
	global_store_dwordx4 v[78:79], v[72:75], off nt
	ds_read_b128 v[72:75], v128 offset:6912
	v_exp_f32_e32 v69, v69
	v_lshl_add_u64 v[76:77], v[76:77], 0, v[64:65]
	v_add_f32_e32 v69, 1.0, v69
	s_waitcnt lgkmcnt(0)
	global_store_dwordx4 v[76:77], v[72:75], off nt
	s_waitcnt lgkmcnt(0)
	s_nop 1
	v_rcp_f32_e32 v73, v69
	s_nop 0
	v_mul_f32_e32 v48, v48, v73
	v_mul_f32_e32 v32, v32, v48
	v_cvt_pk_bf16_f32 v32, v32, s0
	ds_write_b16 v96, v32
	v_mul_f32_e32 v32, 0xbfb8aa3b, v49
	v_exp_f32_e32 v32, v32
	s_nop 0
	v_add_f32_e32 v32, 1.0, v32
	v_rcp_f32_e32 v69, v32
	s_nop 0
	v_mul_f32_e32 v32, v49, v69
	v_mul_f32_e32 v32, v33, v32
	v_cvt_pk_bf16_f32 v32, v32, s0
	ds_write_b16 v96, v32 offset:144
	v_mul_f32_e32 v32, 0xbfb8aa3b, v50
	v_exp_f32_e32 v32, v32
	s_nop 0
	v_add_f32_e32 v32, 1.0, v32
	v_rcp_f32_e32 v48, v32
	s_nop 0
	v_mul_f32_e32 v32, v50, v48
	v_mul_f32_e32 v32, v34, v32
	v_cvt_pk_bf16_f32 v32, v32, s0
	ds_write_b16 v96, v32 offset:288
	v_mul_f32_e32 v32, 0xbfb8aa3b, v51
	v_exp_f32_e32 v32, v32
	s_nop 0
	v_add_f32_e32 v32, 1.0, v32
	v_rcp_f32_e32 v34, v32
	s_nop 0
	v_mul_f32_e32 v32, v51, v34
	v_mul_f32_e32 v32, v35, v32
	v_cvt_pk_bf16_f32 v32, v32, s0
	ds_write_b16 v96, v32 offset:432
	v_mul_f32_e32 v32, 0xbfb8aa3b, v52
	v_exp_f32_e32 v32, v32
	s_nop 0
	v_add_f32_e32 v32, 1.0, v32
	v_rcp_f32_e32 v34, v32
	s_nop 0
	v_mul_f32_e32 v32, v52, v34
	v_mul_f32_e32 v32, v36, v32
	v_cvt_pk_bf16_f32 v32, v32, s0
	ds_write_b16 v96, v32 offset:1152
	v_mul_f32_e32 v32, 0xbfb8aa3b, v53
	v_exp_f32_e32 v32, v32
	s_nop 0
	v_add_f32_e32 v32, 1.0, v32
	v_rcp_f32_e32 v34, v32
	s_nop 0
	v_mul_f32_e32 v32, v53, v34
	v_mul_f32_e32 v32, v37, v32
	v_cvt_pk_bf16_f32 v32, v32, s0
	ds_write_b16 v96, v32 offset:1296
	v_mul_f32_e32 v32, 0xbfb8aa3b, v54
	v_exp_f32_e32 v32, v32
	s_nop 0
	v_add_f32_e32 v32, 1.0, v32
	v_rcp_f32_e32 v34, v32
	s_nop 0
	v_mul_f32_e32 v32, v54, v34
	v_mul_f32_e32 v32, v38, v32
	v_cvt_pk_bf16_f32 v32, v32, s0
	ds_write_b16 v96, v32 offset:1440
	v_mul_f32_e32 v32, 0xbfb8aa3b, v55
	v_exp_f32_e32 v32, v32
	s_nop 0
	v_add_f32_e32 v32, 1.0, v32
	v_rcp_f32_e32 v34, v32
	s_nop 0
	v_mul_f32_e32 v32, v55, v34
	v_mul_f32_e32 v32, v39, v32
	v_cvt_pk_bf16_f32 v32, v32, s0
	ds_write_b16 v96, v32 offset:1584
	v_mul_f32_e32 v32, 0xbfb8aa3b, v56
	v_exp_f32_e32 v32, v32
	s_nop 0
	v_add_f32_e32 v32, 1.0, v32
	v_rcp_f32_e32 v34, v32
	s_nop 0
	v_mul_f32_e32 v32, v56, v34
	v_mul_f32_e32 v32, v40, v32
	v_cvt_pk_bf16_f32 v32, v32, s0
	ds_write_b16 v96, v32 offset:2304
	v_mul_f32_e32 v32, 0xbfb8aa3b, v57
	v_exp_f32_e32 v32, v32
	s_nop 0
	v_add_f32_e32 v32, 1.0, v32
	v_rcp_f32_e32 v34, v32
	s_nop 0
	v_mul_f32_e32 v32, v57, v34
	v_mul_f32_e32 v32, v41, v32
	v_cvt_pk_bf16_f32 v32, v32, s0
	ds_write_b16 v96, v32 offset:2448
	v_mul_f32_e32 v32, 0xbfb8aa3b, v58
	v_exp_f32_e32 v32, v32
	s_nop 0
	v_add_f32_e32 v32, 1.0, v32
	v_rcp_f32_e32 v34, v32
	s_nop 0
	v_mul_f32_e32 v32, v58, v34
	v_mul_f32_e32 v32, v42, v32
	v_cvt_pk_bf16_f32 v32, v32, s0
	ds_write_b16 v96, v32 offset:2592
	v_mul_f32_e32 v32, 0xbfb8aa3b, v59
	v_exp_f32_e32 v32, v32
	s_nop 0
	v_add_f32_e32 v32, 1.0, v32
	v_rcp_f32_e32 v34, v32
	s_nop 0
	v_mul_f32_e32 v32, v59, v34
	v_mul_f32_e32 v32, v43, v32
	v_cvt_pk_bf16_f32 v32, v32, s0
	ds_write_b16 v96, v32 offset:2736
	v_mul_f32_e32 v32, 0xbfb8aa3b, v60
	v_exp_f32_e32 v32, v32
	s_nop 0
	v_add_f32_e32 v32, 1.0, v32
	v_rcp_f32_e32 v34, v32
	s_nop 0
	v_mul_f32_e32 v32, v60, v34
	v_mul_f32_e32 v32, v44, v32
	v_cvt_pk_bf16_f32 v32, v32, s0
	ds_write_b16 v96, v32 offset:3456
	v_mul_f32_e32 v32, 0xbfb8aa3b, v61
	v_exp_f32_e32 v32, v32
	s_nop 0
	v_add_f32_e32 v32, 1.0, v32
	v_rcp_f32_e32 v34, v32
	s_nop 0
	v_mul_f32_e32 v32, v61, v34
	v_mul_f32_e32 v32, v45, v32
	v_cvt_pk_bf16_f32 v32, v32, s0
	ds_write_b16 v96, v32 offset:3600
	v_mul_f32_e32 v32, 0xbfb8aa3b, v62
	v_exp_f32_e32 v32, v32
	s_nop 0
	v_add_f32_e32 v32, 1.0, v32
	v_rcp_f32_e32 v34, v32
	s_nop 0
	v_mul_f32_e32 v32, v62, v34
	v_mul_f32_e32 v32, v46, v32
	v_cvt_pk_bf16_f32 v32, v32, s0
	ds_write_b16 v96, v32 offset:3744
	v_mul_f32_e32 v32, 0xbfb8aa3b, v63
	v_exp_f32_e32 v32, v32
	s_nop 0
	v_add_f32_e32 v32, 1.0, v32
	v_rcp_f32_e32 v34, v32
	s_nop 0
	v_mul_f32_e32 v32, v63, v34
	v_mul_f32_e32 v32, v47, v32
	v_cvt_pk_bf16_f32 v32, v32, s0
	ds_write_b16 v96, v32 offset:3888
	v_mul_f32_e32 v32, 0xbfb8aa3b, v16
	v_exp_f32_e32 v32, v32
	s_nop 0
	v_add_f32_e32 v32, 1.0, v32
	v_rcp_f32_e32 v34, v32
	s_nop 0
	v_mul_f32_e32 v16, v16, v34
	v_mul_f32_e32 v0, v0, v16
	v_cvt_pk_bf16_f32 v0, v0, s0
	ds_write_b16 v96, v0 offset:4608
	v_mul_f32_e32 v0, 0xbfb8aa3b, v17
	v_exp_f32_e32 v0, v0
	s_nop 0
	v_add_f32_e32 v0, 1.0, v0
	v_rcp_f32_e32 v32, v0
	s_nop 0
	v_mul_f32_e32 v0, v17, v32
	v_mul_f32_e32 v0, v1, v0
	v_cvt_pk_bf16_f32 v0, v0, s0
	ds_write_b16 v96, v0 offset:4752
	v_mul_f32_e32 v0, 0xbfb8aa3b, v18
	v_exp_f32_e32 v0, v0
	s_nop 0
	v_add_f32_e32 v0, 1.0, v0
	v_rcp_f32_e32 v16, v0
	s_nop 0
	v_mul_f32_e32 v0, v18, v16
	v_mul_f32_e32 v0, v2, v0
	v_cvt_pk_bf16_f32 v0, v0, s0
	ds_write_b16 v96, v0 offset:4896
	v_mul_f32_e32 v0, 0xbfb8aa3b, v19
	v_exp_f32_e32 v0, v0
	s_nop 0
	v_add_f32_e32 v0, 1.0, v0
	v_rcp_f32_e32 v2, v0
	s_nop 0
	v_mul_f32_e32 v0, v19, v2
	v_mul_f32_e32 v0, v3, v0
	v_cvt_pk_bf16_f32 v0, v0, s0
	ds_write_b16 v96, v0 offset:5040
	v_mul_f32_e32 v0, 0xbfb8aa3b, v20
	v_exp_f32_e32 v0, v0
	s_nop 0
	v_add_f32_e32 v0, 1.0, v0
	v_rcp_f32_e32 v2, v0
	s_nop 0
	v_mul_f32_e32 v0, v20, v2
	v_mul_f32_e32 v0, v4, v0
	v_cvt_pk_bf16_f32 v0, v0, s0
	ds_write_b16 v96, v0 offset:5760
	v_mul_f32_e32 v0, 0xbfb8aa3b, v21
	v_exp_f32_e32 v0, v0
	s_nop 0
	v_add_f32_e32 v0, 1.0, v0
	v_rcp_f32_e32 v2, v0
	s_nop 0
	v_mul_f32_e32 v0, v21, v2
	v_mul_f32_e32 v0, v5, v0
	v_cvt_pk_bf16_f32 v0, v0, s0
	ds_write_b16 v96, v0 offset:5904
	v_mul_f32_e32 v0, 0xbfb8aa3b, v22
	v_exp_f32_e32 v0, v0
	s_nop 0
	v_add_f32_e32 v0, 1.0, v0
	v_rcp_f32_e32 v2, v0
	s_nop 0
	v_mul_f32_e32 v0, v22, v2
	v_mul_f32_e32 v0, v6, v0
	v_cvt_pk_bf16_f32 v0, v0, s0
	ds_write_b16 v96, v0 offset:6048
	v_mul_f32_e32 v0, 0xbfb8aa3b, v23
	v_exp_f32_e32 v0, v0
	s_nop 0
	v_add_f32_e32 v0, 1.0, v0
	v_rcp_f32_e32 v2, v0
	s_nop 0
	v_mul_f32_e32 v0, v23, v2
	v_mul_f32_e32 v0, v7, v0
	v_cvt_pk_bf16_f32 v0, v0, s0
	ds_write_b16 v96, v0 offset:6192
	v_mul_f32_e32 v0, 0xbfb8aa3b, v24
	v_exp_f32_e32 v0, v0
	s_nop 0
	v_add_f32_e32 v0, 1.0, v0
	v_rcp_f32_e32 v2, v0
	s_nop 0
	v_mul_f32_e32 v0, v24, v2
	v_mul_f32_e32 v0, v8, v0
	v_cvt_pk_bf16_f32 v0, v0, s0
	ds_write_b16 v96, v0 offset:6912
	v_mul_f32_e32 v0, 0xbfb8aa3b, v25
	v_exp_f32_e32 v0, v0
	s_nop 0
	v_add_f32_e32 v0, 1.0, v0
	v_rcp_f32_e32 v2, v0
	s_nop 0
	v_mul_f32_e32 v0, v25, v2
	v_mul_f32_e32 v0, v9, v0
	v_cvt_pk_bf16_f32 v0, v0, s0
	ds_write_b16 v96, v0 offset:7056
	v_mul_f32_e32 v0, 0xbfb8aa3b, v26
	v_exp_f32_e32 v0, v0
	s_nop 0
	v_add_f32_e32 v0, 1.0, v0
	v_rcp_f32_e32 v2, v0
	s_nop 0
	v_mul_f32_e32 v0, v26, v2
	v_mul_f32_e32 v0, v10, v0
	v_cvt_pk_bf16_f32 v0, v0, s0
	ds_write_b16 v96, v0 offset:7200
	v_mul_f32_e32 v0, 0xbfb8aa3b, v27
	v_exp_f32_e32 v0, v0
	s_nop 0
	v_add_f32_e32 v0, 1.0, v0
	v_rcp_f32_e32 v2, v0
	s_nop 0
	v_mul_f32_e32 v0, v27, v2
	v_mul_f32_e32 v0, v11, v0
	v_cvt_pk_bf16_f32 v0, v0, s0
	ds_write_b16 v96, v0 offset:7344
	v_mul_f32_e32 v0, 0xbfb8aa3b, v28
	v_exp_f32_e32 v0, v0
	s_nop 0
	v_add_f32_e32 v0, 1.0, v0
	v_rcp_f32_e32 v2, v0
	s_nop 0
	v_mul_f32_e32 v0, v28, v2
	v_mul_f32_e32 v0, v12, v0
	v_cvt_pk_bf16_f32 v0, v0, s0
	ds_write_b16 v96, v0 offset:8064
	v_mul_f32_e32 v0, 0xbfb8aa3b, v29
	v_exp_f32_e32 v0, v0
	s_nop 0
	v_add_f32_e32 v0, 1.0, v0
	v_rcp_f32_e32 v2, v0
	s_nop 0
	v_mul_f32_e32 v0, v29, v2
	v_mul_f32_e32 v0, v13, v0
	v_cvt_pk_bf16_f32 v0, v0, s0
	ds_write_b16 v96, v0 offset:8208
	v_mul_f32_e32 v0, 0xbfb8aa3b, v30
	v_exp_f32_e32 v0, v0
	s_nop 0
	v_add_f32_e32 v0, 1.0, v0
	v_rcp_f32_e32 v2, v0
	s_nop 0
	v_mul_f32_e32 v0, v30, v2
	v_mul_f32_e32 v0, v14, v0
	v_cvt_pk_bf16_f32 v0, v0, s0
	ds_write_b16 v96, v0 offset:8352
	v_mul_f32_e32 v0, 0xbfb8aa3b, v31
	v_exp_f32_e32 v0, v0
	s_nop 0
	v_add_f32_e32 v0, 1.0, v0
	v_rcp_f32_e32 v2, v0
	s_nop 0
	v_mul_f32_e32 v0, v31, v2
	v_mul_f32_e32 v0, v15, v0
	v_cvt_pk_bf16_f32 v0, v0, s0
	ds_write_b16 v96, v0 offset:8496
	v_or_b32_e32 v4, 2, v68
	s_waitcnt lgkmcnt(0)
	v_ashrrev_i32_e32 v5, 31, v4
	ds_read_b128 v[0:3], v128
	v_mad_i64_i32 v[6:7], s[0:1], v71, s23, v[4:5]
	v_lshlrev_b64 v[6:7], 10, v[6:7]
	v_lshl_add_u64 v[6:7], s[66:67], 0, v[6:7]
	v_lshl_add_u64 v[6:7], v[6:7], 0, v[176:177]
	v_lshl_add_u64 v[8:9], v[6:7], 0, v[66:67]
	s_waitcnt lgkmcnt(0)
	global_store_dwordx4 v[8:9], v[0:3], off nt
	ds_read_b128 v[0:3], v128 offset:2304
	v_lshl_add_u64 v[6:7], v[6:7], 0, v[64:65]
	v_mad_i64_i32 v[4:5], s[0:1], v70, s23, v[4:5]
	v_lshlrev_b64 v[4:5], 10, v[4:5]
	s_waitcnt lgkmcnt(0)
	global_store_dwordx4 v[6:7], v[0:3], off nt
	ds_read_b128 v[0:3], v128 offset:4608
	v_lshl_add_u64 v[4:5], s[66:67], 0, v[4:5]
	v_lshl_add_u64 v[4:5], v[4:5], 0, v[176:177]
	v_lshl_add_u64 v[6:7], v[4:5], 0, v[66:67]
	v_lshl_add_u64 v[4:5], v[4:5], 0, v[64:65]
	s_waitcnt lgkmcnt(0)
	global_store_dwordx4 v[6:7], v[0:3], off nt
	ds_read_b128 v[0:3], v128 offset:6912
	v_readlane_b32 s0, v254, 11
	s_add_i32 s2, s2, s0
	s_cmp_lt_i32 s2, s3
	s_waitcnt lgkmcnt(0)
	global_store_dwordx4 v[4:5], v[0:3], off nt
	s_waitcnt lgkmcnt(0)
	s_barrier
	s_cbranch_scc1 .LBB0_1031
